# P5 selected branch: four LDS stage slots (dead Q staging area reused), one workgroup barrier per two 64-key stages instead of one per stage
# speedup vs baseline: 1.0088x; 1.0088x over previous
.LBB0_750:
	v_and_b32_e32 v7, 15, v8
	v_bfe_u32 v11, v8, 4, 2
	v_lshlrev_b32_e32 v9, 7, v9
	v_xor_b32_e32 v10, v10, v8
	s_movk_i32 s2, 0x70
	v_and_or_b32 v242, v10, s2, v9
	v_mul_u32_u24_e32 v10, 0x90, v7
	v_lshlrev_b32_e32 v12, 4, v11
	v_add3_u32 v10, v199, v10, v12
	ds_read_b128 v[104:107], v10 offset:32768
	ds_read_b128 v[108:111], v10 offset:32832
	ds_read_b128 v[112:115], v10 offset:35072
	ds_read_b128 v[116:119], v10 offset:35136
	ds_read_b128 v[120:123], v10 offset:37376
	ds_read_b128 v[124:127], v10 offset:37440
	ds_read_b128 v[130:133], v10 offset:39680
	ds_read_b128 v[134:137], v10 offset:39744
	v_lshrrev_b32_e32 v9, 2, v8
	v_and_b32_e32 v9, 12, v9
	s_movk_i32 s2, 0x1320
	v_lshrrev_b32_e64 v9, v9, s2
	v_xor_b32_e32 v9, v9, v8
	v_lshlrev_b32_e32 v6, 6, v6
	v_lshlrev_b32_e32 v9, 4, v9
	v_readfirstlane_b32 s26, v198
	v_mov_b32_e32 v138, 0x3f803f80
	v_and_or_b32 v243, v9, 48, v6
	s_cmp_lt_u32 s69, 2
	s_waitcnt vmcnt(3)
	ds_write_b128 v242, v[56:59]
	s_waitcnt vmcnt(2)
	ds_write_b128 v242, v[68:71] offset:8192
	s_waitcnt vmcnt(1)
	ds_write_b128 v243, v[84:87] offset:4096
	s_waitcnt vmcnt(0)
	ds_write_b128 v243, v[96:99] offset:12288
	ds_write_b128 v242, v[76:79] offset:16384
	ds_write_b128 v242, v[80:83] offset:24576
	ds_write_b128 v243, v[88:91] offset:20480
	ds_write_b128 v243, v[92:95] offset:28672
	s_cbranch_scc1 .LBB0_752
	v_add_co_u32_e32 v12, vcc, 0xc0000, v2
	s_nop 1
	v_addc_co_u32_e32 v13, vcc, 0, v3, vcc
	v_add_co_u32_e32 v2, vcc, 0xf0000, v2
	s_nop 1
	v_addc_co_u32_e32 v3, vcc, 0, v3, vcc
	global_load_dwordx4 v[56:59], v[12:13], off
	global_load_dwordx4 v[68:71], v[2:3], off
	v_add_co_u32_e32 v12, vcc, 0x30000, v2
	s_nop 1
	v_addc_co_u32_e32 v13, vcc, 0, v3, vcc
	v_add_co_u32_e32 v14, vcc, 0x60000, v2
	s_nop 1
	v_addc_co_u32_e32 v15, vcc, 0, v3, vcc
	v_add_co_u32_e32 v2, vcc, 0x4000, v4
	s_nop 1
	v_addc_co_u32_e32 v3, vcc, 0, v5, vcc
	global_load_dwordx4 v[84:87], v[2:3], off
	global_load_dwordx4 v[96:99], v[2:3], off offset:64
	global_load_dwordx4 v[76:79], v[12:13], off
	global_load_dwordx4 v[80:83], v[14:15], off
	v_add_co_u32_e32 v12, vcc, 0x6000, v4
	s_nop 1
	v_addc_co_u32_e32 v13, vcc, 0, v5, vcc
	global_load_dwordx4 v[88:91], v[12:13], off
	global_load_dwordx4 v[92:95], v[12:13], off offset:64

.LBB0_755:
	s_addk_i32 s28, 0x80
	s_add_i32 s27, s27, 2
	s_add_i32 s29, s29, -1
	s_cmp_le_u32 s29, s69
	v_lshl_add_u64 v[198:199], v[198:199], 0, s[0:1]
	s_cbranch_scc0 .LBB0_638
	s_branch .LB2_756
.LBB0_756:
	s_add_i32 s42, s27, -4
	s_cmp_lt_u32 s42, s69
	s_cselect_b64 s[40:41], -1, 0
	s_add_i32 s2, s27, -2
	s_cmp_gt_u32 s2, s69
	s_cbranch_scc1 .LqA_w0done
	s_add_i32 s2, s27, -1
	s_cmp_le_u32 s2, s69
	s_cbranch_scc1 .LqA_w0relax
	s_waitcnt vmcnt(3)
	ds_write_b128 v242, v[56:59] offset:32768
	s_waitcnt vmcnt(2)
	ds_write_b128 v242, v[68:71] offset:40960
	s_waitcnt vmcnt(1)
	ds_write_b128 v243, v[84:87] offset:36864
	s_waitcnt vmcnt(0)
	ds_write_b128 v243, v[96:99] offset:45056
	s_branch .LqA_w0done
.LqA_w0relax:
	s_waitcnt vmcnt(7)
	ds_write_b128 v242, v[56:59] offset:32768
	s_waitcnt vmcnt(6)
	ds_write_b128 v242, v[68:71] offset:40960
	s_waitcnt vmcnt(5)
	ds_write_b128 v243, v[84:87] offset:36864
	s_waitcnt vmcnt(4)
	ds_write_b128 v243, v[96:99] offset:45056
.LqA_w0done:
	s_add_i32 s29, s42, 3
	s_cmp_gt_u32 s27, s69
	s_cbranch_scc1 .LBB0_760
	s_sub_i32 s2, s28, 32
	v_mad_u64_u32 v[0:1], s[2:3], s2, v239, v[208:209]
	v_mad_u64_u32 v[2:3], s[2:3], s28, v239, v[208:209]
	global_load_dwordx4 v[56:59], v[0:1], off offset:3584
	global_load_dwordx4 v[68:71], v[2:3], off offset:3584
	v_add_co_u32_e32 v0, vcc, 0x2000, v198
	s_nop 1
	v_addc_co_u32_e32 v1, vcc, 0, v199, vcc
	global_load_dwordx4 v[84:87], v[0:1], off
	global_load_dwordx4 v[96:99], v[0:1], off offset:64

.LBB0_810:
	s_waitcnt lgkmcnt(0)
	s_andn2_b64 vcc, exec, s[40:41]
	s_cbranch_vccnz .LBB0_754
	s_add_i32 s2, s27, -1
	s_cmp_gt_u32 s2, s69
	s_cbranch_scc1 .LqA_w1done
	s_cmp_le_u32 s27, s69
	s_cbranch_scc1 .LqA_w1relax
	s_waitcnt vmcnt(3)
	ds_write_b128 v242, v[76:79] offset:49152
	s_waitcnt vmcnt(2)
	ds_write_b128 v242, v[80:83] offset:57344
	s_waitcnt vmcnt(1)
	ds_write_b128 v243, v[88:91] offset:53248
	s_waitcnt vmcnt(0)
	ds_write_b128 v243, v[92:95] offset:61440
	s_branch .LqA_w1done
.LqA_w1relax:
	s_waitcnt vmcnt(7)
	ds_write_b128 v242, v[76:79] offset:49152
	s_waitcnt vmcnt(6)
	ds_write_b128 v242, v[80:83] offset:57344
	s_waitcnt vmcnt(5)
	ds_write_b128 v243, v[88:91] offset:53248
	s_waitcnt vmcnt(4)
	ds_write_b128 v243, v[92:95] offset:61440
.LqA_w1done:
	s_add_i32 s2, s27, 1
	s_cmp_gt_u32 s2, s69
	s_cbranch_scc1 .LBB0_815
	s_add_i32 s2, s28, 32
	v_mad_u64_u32 v[0:1], s[2:3], s2, v239, v[208:209]
	s_add_i32 s2, s28, 64
	s_nop 0
	v_mad_u64_u32 v[2:3], s[2:3], s2, v239, v[208:209]
	global_load_dwordx4 v[76:79], v[0:1], off offset:3584
	global_load_dwordx4 v[80:83], v[2:3], off offset:3584
	v_add_co_u32_e32 v0, vcc, 0x4000, v198
	s_nop 1
	v_addc_co_u32_e32 v1, vcc, 0, v199, vcc
	global_load_dwordx4 v[88:91], v[0:1], off
	global_load_dwordx4 v[92:95], v[0:1], off offset:64

.LBB0_862:
	s_andn2_b64 vcc, exec, s[40:41]
	s_cbranch_vccnz .LBB0_753
	v_add_u32_e32 v174, s28, v240
	v_add_u32_e32 v174, 0xffffbf74, v174
	s_nop 0
	v_cmp_gt_i32_e32 vcc, 1, v174
	s_nop 1
	v_cndmask_b32_e32 v0, 0, v0, vcc
	v_cmp_gt_i32_e32 vcc, 0, v174
	s_nop 1
	v_cndmask_b32_e32 v1, 0, v1, vcc
	v_cmp_gt_i32_e32 vcc, -1, v174
	s_nop 1
	v_cndmask_b32_e32 v2, 0, v2, vcc
	v_cmp_gt_i32_e32 vcc, -2, v174
	s_nop 1
	v_cndmask_b32_e32 v3, 0, v3, vcc
	v_cmp_gt_i32_e32 vcc, -15, v174
	s_nop 1
	v_cndmask_b32_e32 v4, 0, v4, vcc
	v_cmp_gt_i32_e32 vcc, -16, v174
	s_nop 1
	v_cndmask_b32_e32 v5, 0, v5, vcc
	v_cmp_gt_i32_e32 vcc, s14, v174
	s_nop 1
	v_cndmask_b32_e32 v6, 0, v6, vcc
	v_cmp_gt_i32_e32 vcc, s15, v174
	s_nop 1
	v_cndmask_b32_e32 v7, 0, v7, vcc
	s_branch .LBB0_753
.LB2_753:
	v_cvt_pk_bf16_f32 v0, v0, v1
	v_cvt_pk_bf16_f32 v1, v2, v3
	v_cvt_pk_bf16_f32 v2, v4, v5
	v_cvt_pk_bf16_f32 v3, v6, v7
	v_cndmask_b32_e64 v0, 0, v0, s[42:43]
	v_cndmask_b32_e64 v1, 0, v1, s[42:43]
	v_cndmask_b32_e64 v2, 0, v2, s[42:43]
	v_cndmask_b32_e64 v3, 0, v3, s[42:43]
	s_waitcnt lgkmcnt(3)
	s_nop 0
	v_mfma_f32_16x16x32_bf16 v[20:23], v[158:161], v[0:3], v[20:23]
	s_waitcnt lgkmcnt(2)
	v_mfma_f32_16x16x32_bf16 v[16:19], v[162:165], v[0:3], v[16:19]
	s_waitcnt lgkmcnt(1)
	v_mfma_f32_16x16x32_bf16 v[12:15], v[166:169], v[0:3], v[12:15]
	s_waitcnt lgkmcnt(0)
	v_mfma_f32_16x16x32_bf16 v[8:11], v[170:173], v[0:3], v[8:11]
	v_mfma_f32_16x16x32_bf16 v[142:145], v[138:141], v[0:3], v[142:145]

.LB2_756:
	s_add_i32 s42, s27, -4
	s_cmp_lt_u32 s42, s69
	s_cselect_b64 s[40:41], -1, 0
	s_add_i32 s2, s27, -2
	s_cmp_gt_u32 s2, s69
	s_cbranch_scc1 .LqB_w0done
	s_add_i32 s2, s27, -1
	s_cmp_le_u32 s2, s69
	s_cbranch_scc1 .LqB_w0relax
	s_waitcnt vmcnt(3)
	ds_write_b128 v242, v[56:59]
	s_waitcnt vmcnt(2)
	ds_write_b128 v242, v[68:71] offset:8192
	s_waitcnt vmcnt(1)
	ds_write_b128 v243, v[84:87] offset:4096
	s_waitcnt vmcnt(0)
	ds_write_b128 v243, v[96:99] offset:12288
	s_branch .LqB_w0done
.LqB_w0relax:
	s_waitcnt vmcnt(7)
	ds_write_b128 v242, v[56:59]
	s_waitcnt vmcnt(6)
	ds_write_b128 v242, v[68:71] offset:8192
	s_waitcnt vmcnt(5)
	ds_write_b128 v243, v[84:87] offset:4096
	s_waitcnt vmcnt(4)
	ds_write_b128 v243, v[96:99] offset:12288

.Lsel_have_words2:
	v_and_b32_e32 v0, s70, v250
	v_cmp_ne_u32_e64 s[50:51], 0, v0
	v_and_b32_e32 v0, s70, v251
	v_cmp_ne_u32_e64 s[48:49], 0, v0
	v_and_b32_e32 v0, s70, v249
	v_cmp_ne_u32_e64 s[46:47], 0, v0
	v_and_b32_e32 v0, s70, v248
	v_cmp_ne_u32_e64 s[42:43], 0, v0
	s_mov_b64 s[86:87], s[50:51]
	s_mov_b64 s[88:89], s[48:49]
	s_mov_b64 s[90:91], s[46:47]
	s_mov_b64 s[92:93], s[42:43]
	s_or_b64 s[2:3], s[48:49], s[50:51]
	s_or_b64 s[2:3], s[2:3], s[46:47]
	s_or_b64 s[2:3], s[2:3], s[42:43]
	s_cmp_eq_u64 s[2:3], 0
	s_cbranch_scc1 .LB2_785
	ds_read_b128 v[182:185], v246 offset:32768
	ds_read_b128 v[178:181], v246 offset:34816
	ds_read_b128 v[186:189], v247 offset:32768
	ds_read_b128 v[174:177], v247 offset:34816
	ds_read_b128 v[158:161], v244 offset:36864
	ds_read_b128 v[162:165], v244 offset:37888
	ds_read_b128 v[166:169], v244 offset:38912
	ds_read_b128 v[170:173], v244 offset:39936
	s_add_i32 s2, s28, 0xfffffeff
	s_cmp_le_i32 s2, s26
	s_cselect_b64 s[2:3], -1, 0
	v_cndmask_b32_e64 v0, 0, 1, s[2:3]
	s_cmp_eq_u64 s[50:51], 0
	v_cmp_ne_u32_e64 s[44:45], 1, v0
	s_cbranch_scc1 .LB2_767
	s_waitcnt lgkmcnt(7)
	v_mfma_f32_16x16x32_bf16 v[0:3], v[182:185], v[104:107], 0
	s_and_b64 vcc, exec, s[44:45]
	s_mov_b64 s[64:65], -1
	s_waitcnt lgkmcnt(6)
	v_mfma_f32_16x16x32_bf16 v[4:7], v[178:181], v[104:107], 0
	s_waitcnt lgkmcnt(5)
	v_mfma_f32_16x16x32_bf16 v[0:3], v[186:189], v[108:111], v[0:3]
	s_waitcnt lgkmcnt(4)
	v_mfma_f32_16x16x32_bf16 v[4:7], v[174:177], v[108:111], v[4:7]
	s_nop 5
	v_exp_f32_e32 v0, v0
	v_exp_f32_e32 v1, v1
	v_exp_f32_e32 v2, v2
	v_exp_f32_e32 v3, v3
	v_exp_f32_e32 v4, v4
	v_exp_f32_e32 v5, v5
	v_exp_f32_e32 v6, v6
	v_exp_f32_e32 v7, v7
	s_cbranch_vccnz .LB2_764
	s_mov_b64 s[64:65], 0

.LB2_785:
	s_mov_b64 s[50:51], s[86:87]
	s_mov_b64 s[48:49], s[88:89]
	s_mov_b64 s[46:47], s[90:91]
	s_mov_b64 s[42:43], s[92:93]
	s_or_b64 s[2:3], s[48:49], s[50:51]
	s_or_b64 s[2:3], s[2:3], s[46:47]
	s_or_b64 s[2:3], s[2:3], s[42:43]
	s_cmp_eq_u64 s[2:3], 0
	s_cbranch_scc1 .LB2_810
	ds_read_b128 v[182:185], v246 offset:40960
	ds_read_b128 v[178:181], v246 offset:43008
	ds_read_b128 v[186:189], v247 offset:40960
	ds_read_b128 v[174:177], v247 offset:43008
	ds_read_b128 v[158:161], v244 offset:45056
	ds_read_b128 v[162:165], v244 offset:46080
	ds_read_b128 v[166:169], v244 offset:47104
	ds_read_b128 v[170:173], v244 offset:48128
	s_add_i32 s2, s28, 0xffffff1f
	s_cmp_le_i32 s2, s26
	s_cselect_b64 s[2:3], -1, 0
	v_cndmask_b32_e64 v0, 0, 1, s[2:3]
	s_cmp_eq_u64 s[50:51], 0
	v_cmp_ne_u32_e64 s[44:45], 1, v0
	s_cbranch_scc1 .LB2_792
	s_waitcnt lgkmcnt(7)
	v_mfma_f32_16x16x32_bf16 v[0:3], v[182:185], v[104:107], 0
	s_and_b64 vcc, exec, s[44:45]
	s_mov_b64 s[64:65], -1
	s_waitcnt lgkmcnt(6)
	v_mfma_f32_16x16x32_bf16 v[4:7], v[178:181], v[104:107], 0
	s_waitcnt lgkmcnt(5)
	v_mfma_f32_16x16x32_bf16 v[0:3], v[186:189], v[108:111], v[0:3]
	s_waitcnt lgkmcnt(4)
	v_mfma_f32_16x16x32_bf16 v[4:7], v[174:177], v[108:111], v[4:7]
	s_nop 5
	v_exp_f32_e32 v0, v0
	v_exp_f32_e32 v1, v1
	v_exp_f32_e32 v2, v2
	v_exp_f32_e32 v3, v3
	v_exp_f32_e32 v4, v4
	v_exp_f32_e32 v5, v5
	v_exp_f32_e32 v6, v6
	v_exp_f32_e32 v7, v7
	s_cbranch_vccnz .LB2_789
	s_mov_b64 s[64:65], 0

.LB2_810:
	s_waitcnt lgkmcnt(0)
	s_andn2_b64 vcc, exec, s[40:41]
	s_cbranch_vccnz .LB2_754
	s_add_i32 s2, s27, -1
	s_cmp_gt_u32 s2, s69
	s_cbranch_scc1 .LqB_w1done
	s_cmp_le_u32 s27, s69
	s_cbranch_scc1 .LqB_w1relax
	s_waitcnt vmcnt(3)
	ds_write_b128 v242, v[76:79] offset:16384
	s_waitcnt vmcnt(2)
	ds_write_b128 v242, v[80:83] offset:24576
	s_waitcnt vmcnt(1)
	ds_write_b128 v243, v[88:91] offset:20480
	s_waitcnt vmcnt(0)
	ds_write_b128 v243, v[92:95] offset:28672
	s_branch .LqB_w1done
.LqB_w1relax:
	s_waitcnt vmcnt(7)
	ds_write_b128 v242, v[76:79] offset:16384
	s_waitcnt vmcnt(6)
	ds_write_b128 v242, v[80:83] offset:24576
	s_waitcnt vmcnt(5)
	ds_write_b128 v243, v[88:91] offset:20480
	s_waitcnt vmcnt(4)
	ds_write_b128 v243, v[92:95] offset:28672

.LB2_815:
	s_add_i32 s2, s27, -3
	s_lshl_b32 s64, 1, s2
	v_and_b32_e32 v0, s64, v250
	v_cmp_ne_u32_e64 s[50:51], 0, v0
	v_and_b32_e32 v0, s64, v251
	v_cmp_ne_u32_e64 s[48:49], 0, v0
	v_and_b32_e32 v0, s64, v249
	v_cmp_ne_u32_e64 s[46:47], 0, v0
	v_and_b32_e32 v0, s64, v248
	v_cmp_ne_u32_e64 s[42:43], 0, v0
	s_mov_b64 s[86:87], s[50:51]
	s_mov_b64 s[88:89], s[48:49]
	s_mov_b64 s[90:91], s[46:47]
	s_mov_b64 s[92:93], s[42:43]
	s_or_b64 s[2:3], s[48:49], s[50:51]
	s_or_b64 s[2:3], s[2:3], s[46:47]
	s_or_b64 s[2:3], s[2:3], s[42:43]
	s_cmp_eq_u64 s[2:3], 0
	s_cbranch_scc1 .LB2_840
	ds_read_b128 v[182:185], v246 offset:49152
	ds_read_b128 v[178:181], v246 offset:51200
	ds_read_b128 v[186:189], v247 offset:49152
	ds_read_b128 v[174:177], v247 offset:51200
	ds_read_b128 v[158:161], v244 offset:53248
	ds_read_b128 v[162:165], v244 offset:54272
	ds_read_b128 v[166:169], v244 offset:55296
	ds_read_b128 v[170:173], v244 offset:56320
	s_add_i32 s2, s28, 0xffffff3f
	s_cmp_le_i32 s2, s26
	s_cselect_b64 s[2:3], -1, 0
	v_cndmask_b32_e64 v0, 0, 1, s[2:3]
	s_cmp_eq_u64 s[50:51], 0
	v_cmp_ne_u32_e64 s[44:45], 1, v0
	s_cbranch_scc1 .LB2_822
	s_waitcnt lgkmcnt(7)
	v_mfma_f32_16x16x32_bf16 v[0:3], v[182:185], v[104:107], 0
	s_and_b64 vcc, exec, s[44:45]
	s_mov_b64 s[40:41], -1
	s_waitcnt lgkmcnt(6)
	v_mfma_f32_16x16x32_bf16 v[4:7], v[178:181], v[104:107], 0
	s_waitcnt lgkmcnt(5)
	v_mfma_f32_16x16x32_bf16 v[0:3], v[186:189], v[108:111], v[0:3]
	s_waitcnt lgkmcnt(4)
	v_mfma_f32_16x16x32_bf16 v[4:7], v[174:177], v[108:111], v[4:7]
	s_nop 5
	v_exp_f32_e32 v0, v0
	v_exp_f32_e32 v1, v1
	v_exp_f32_e32 v2, v2
	v_exp_f32_e32 v3, v3
	v_exp_f32_e32 v4, v4
	v_exp_f32_e32 v5, v5
	v_exp_f32_e32 v6, v6
	v_exp_f32_e32 v7, v7
	s_cbranch_vccnz .LB2_819
	s_mov_b64 s[40:41], 0

.LB2_840:
	s_mov_b64 s[50:51], s[86:87]
	s_mov_b64 s[48:49], s[88:89]
	s_mov_b64 s[46:47], s[90:91]
	s_mov_b64 s[42:43], s[92:93]
	s_or_b64 s[2:3], s[48:49], s[50:51]
	s_or_b64 s[2:3], s[2:3], s[46:47]
	s_or_b64 s[2:3], s[2:3], s[42:43]
	s_cmp_eq_u64 s[2:3], 0
	s_cbranch_scc1 .LB2_754
	ds_read_b128 v[182:185], v246 offset:57344
	ds_read_b128 v[178:181], v246 offset:59392
	ds_read_b128 v[186:189], v247 offset:57344
	ds_read_b128 v[174:177], v247 offset:59392
	ds_read_b128 v[158:161], v244 offset:61440
	ds_read_b128 v[162:165], v244 offset:62464
	ds_read_b128 v[166:169], v244 offset:63488
	ds_read_b128 v[170:173], v244 offset:64512
	s_add_i32 s2, s28, 0xffffff5f
	s_cmp_le_i32 s2, s26
	s_cselect_b64 s[2:3], -1, 0
	v_cndmask_b32_e64 v0, 0, 1, s[2:3]
	s_cmp_eq_u64 s[50:51], 0
	v_cmp_ne_u32_e64 s[44:45], 1, v0
	s_cbranch_scc1 .LB2_847
	s_waitcnt lgkmcnt(7)
	v_mfma_f32_16x16x32_bf16 v[0:3], v[182:185], v[104:107], 0
	s_and_b64 vcc, exec, s[44:45]
	s_mov_b64 s[40:41], -1
	s_waitcnt lgkmcnt(6)
	v_mfma_f32_16x16x32_bf16 v[4:7], v[178:181], v[104:107], 0
	s_waitcnt lgkmcnt(5)
	v_mfma_f32_16x16x32_bf16 v[0:3], v[186:189], v[108:111], v[0:3]
	s_waitcnt lgkmcnt(4)
	v_mfma_f32_16x16x32_bf16 v[4:7], v[174:177], v[108:111], v[4:7]
	s_nop 5
	v_exp_f32_e32 v0, v0
	v_exp_f32_e32 v1, v1
	v_exp_f32_e32 v2, v2
	v_exp_f32_e32 v3, v3
	v_exp_f32_e32 v4, v4
	v_exp_f32_e32 v5, v5
	v_exp_f32_e32 v6, v6
	v_exp_f32_e32 v7, v7
	s_cbranch_vccnz .LB2_844
	s_mov_b64 s[40:41], 0
